# diff_attn unit finalisation: 8 sub-LN gain loads issued together instead of 8 serialized load/wait/store round trips
# speedup vs baseline: 1.0028x; 1.0028x over previous
.Ldf_nodrain:
	s_waitcnt vmcnt(0)
	s_and_saveexec_b64 s[6:7], s[0:1]
	s_xor_b64 s[0:1], exec, s[6:7]
	s_cbranch_execz .LBB0_1582
	v_div_scale_f32 v0, s[6:7], v88, v88, 1.0
	v_rcp_f32_e32 v2, v0
	v_div_scale_f32 v3, vcc, 1.0, v88, 1.0
	v_readlane_b32 s36, v255, 2
	v_fma_f32 v4, -v0, v2, 1.0
	v_fmac_f32_e32 v2, v4, v2
	v_mul_f32_e32 v4, v3, v2
	v_fma_f32 v5, -v0, v4, v3
	v_fmac_f32_e32 v4, v5, v2
	v_fma_f32 v0, -v0, v4, v3
	v_div_scale_f32 v3, s[6:7], v76, v76, v141
	v_rcp_f32_e32 v5, v3
	v_div_fmas_f32 v0, v0, v2, v4
	v_div_fixup_f32 v0, v0, v88, 1.0
	v_readlane_b32 s50, v255, 16
	v_fma_f32 v2, -v3, v5, 1.0
	v_fmac_f32_e32 v5, v2, v5
	v_div_scale_f32 v2, vcc, v141, v76, v141
	v_mul_f32_e32 v4, v2, v5
	v_fma_f32 v6, -v3, v4, v2
	v_fmac_f32_e32 v4, v6, v5
	v_fma_f32 v2, -v3, v4, v2
	v_div_fmas_f32 v2, v2, v5, v4
	v_div_fixup_f32 v6, v2, v76, v141
	v_pk_mul_f32 v[2:3], v[80:81], v[6:7] op_sel_hi:[1,0]
	v_readlane_b32 s51, v255, 17
	v_pk_fma_f32 v[8:9], v[84:85], v[0:1], v[2:3] op_sel_hi:[1,0,1] neg_lo:[0,0,1] neg_hi:[0,0,1]
	v_pk_mul_f32 v[2:3], v[82:83], v[6:7] op_sel_hi:[1,0]
	v_pk_mul_f32 v[66:67], v[66:67], v[6:7] op_sel_hi:[1,0]
	v_pk_fma_f32 v[12:13], v[86:87], v[0:1], v[2:3] op_sel_hi:[1,0,1] neg_lo:[0,0,1] neg_hi:[0,0,1]
	v_pk_mul_f32 v[2:3], v[74:75], v[6:7] op_sel_hi:[1,0]
	v_pk_mul_f32 v[64:65], v[64:65], v[6:7] op_sel_hi:[1,0]
	v_pk_fma_f32 v[16:17], v[70:71], v[0:1], v[2:3] op_sel_hi:[1,0,1] neg_lo:[0,0,1] neg_hi:[0,0,1]
	global_load_dwordx4 v[182:185], v108, s[50:51]
	global_load_dwordx4 v[186:189], v108, s[50:51] offset:64
	global_load_dwordx4 v[190:193], v108, s[50:51] offset:128
	global_load_dwordx4 v[194:197], v108, s[50:51] offset:192
	global_load_dwordx4 v[198:201], v108, s[50:51] offset:256
	global_load_dwordx4 v[202:205], v108, s[50:51] offset:320
	global_load_dwordx4 v[206:209], v108, s[50:51] offset:384
	global_load_dwordx4 v[210:213], v108, s[50:51] offset:448
	v_pk_mul_f32 v[70:71], v[72:73], v[6:7] op_sel_hi:[1,0]
	v_pk_mul_f32 v[58:59], v[58:59], v[6:7] op_sel_hi:[1,0]
	v_pk_fma_f32 v[68:69], v[68:69], v[0:1], v[70:71] op_sel_hi:[1,0,1] neg_lo:[0,0,1] neg_hi:[0,0,1]
	v_pk_mul_f32 v[56:57], v[56:57], v[6:7] op_sel_hi:[1,0]
	v_pk_mul_f32 v[70:71], v[68:69], v[68:69]
	v_pk_mul_f32 v[50:51], v[50:51], v[6:7] op_sel_hi:[1,0]
	v_pk_mul_f32 v[48:49], v[48:49], v[6:7] op_sel_hi:[1,0]
	v_pk_mul_f32 v[42:43], v[42:43], v[6:7] op_sel_hi:[1,0]
	v_pk_mul_f32 v[40:41], v[40:41], v[6:7] op_sel_hi:[1,0]
	v_pk_mul_f32 v[30:31], v[30:31], v[6:7] op_sel_hi:[1,0]
	v_pk_mul_f32 v[28:29], v[28:29], v[6:7] op_sel_hi:[1,0]
	v_pk_mul_f32 v[22:23], v[22:23], v[6:7] op_sel_hi:[1,0]
	v_pk_mul_f32 v[6:7], v[20:21], v[6:7] op_sel_hi:[1,0]
	v_pk_mul_f32 v[18:19], v[16:17], v[16:17]
	v_pk_fma_f32 v[62:63], v[62:63], v[0:1], v[66:67] op_sel_hi:[1,0,1] neg_lo:[0,0,1] neg_hi:[0,0,1]
	v_pk_fma_f32 v[60:61], v[60:61], v[0:1], v[64:65] op_sel_hi:[1,0,1] neg_lo:[0,0,1] neg_hi:[0,0,1]
	v_pk_fma_f32 v[54:55], v[54:55], v[0:1], v[58:59] op_sel_hi:[1,0,1] neg_lo:[0,0,1] neg_hi:[0,0,1]
	v_pk_fma_f32 v[52:53], v[52:53], v[0:1], v[56:57] op_sel_hi:[1,0,1] neg_lo:[0,0,1] neg_hi:[0,0,1]
	v_pk_fma_f32 v[46:47], v[46:47], v[0:1], v[50:51] op_sel_hi:[1,0,1] neg_lo:[0,0,1] neg_hi:[0,0,1]
	v_pk_fma_f32 v[44:45], v[44:45], v[0:1], v[48:49] op_sel_hi:[1,0,1] neg_lo:[0,0,1] neg_hi:[0,0,1]
	v_pk_fma_f32 v[38:39], v[38:39], v[0:1], v[42:43] op_sel_hi:[1,0,1] neg_lo:[0,0,1] neg_hi:[0,0,1]
	v_pk_fma_f32 v[36:37], v[36:37], v[0:1], v[40:41] op_sel_hi:[1,0,1] neg_lo:[0,0,1] neg_hi:[0,0,1]
	v_pk_fma_f32 v[30:31], v[34:35], v[0:1], v[30:31] op_sel_hi:[1,0,1] neg_lo:[0,0,1] neg_hi:[0,0,1]
	v_pk_fma_f32 v[28:29], v[32:33], v[0:1], v[28:29] op_sel_hi:[1,0,1] neg_lo:[0,0,1] neg_hi:[0,0,1]
	v_pk_fma_f32 v[22:23], v[26:27], v[0:1], v[22:23] op_sel_hi:[1,0,1] neg_lo:[0,0,1] neg_hi:[0,0,1]
	v_pk_fma_f32 v[6:7], v[24:25], v[0:1], v[6:7] op_sel_hi:[1,0,1] neg_lo:[0,0,1] neg_hi:[0,0,1]
	v_add_f32_e32 v0, v70, v71
	v_add_f32_e32 v0, v18, v0
	v_pk_mul_f32 v[64:65], v[60:61], v[60:61]
	v_add_f32_e32 v0, v19, v0
	v_add_f32_e32 v0, v64, v0
	v_pk_mul_f32 v[66:67], v[62:63], v[62:63]
	v_add_f32_e32 v0, v65, v0
	v_add_f32_e32 v0, v66, v0
	v_pk_mul_f32 v[56:57], v[52:53], v[52:53]
	v_add_f32_e32 v0, v67, v0
	v_add_f32_e32 v0, v56, v0
	v_pk_mul_f32 v[58:59], v[54:55], v[54:55]
	v_add_f32_e32 v0, v57, v0
	v_add_f32_e32 v0, v58, v0
	v_pk_mul_f32 v[48:49], v[44:45], v[44:45]
	v_add_f32_e32 v0, v59, v0
	v_add_f32_e32 v0, v48, v0
	v_pk_mul_f32 v[50:51], v[46:47], v[46:47]
	v_add_f32_e32 v0, v49, v0
	v_add_f32_e32 v0, v50, v0
	v_pk_mul_f32 v[40:41], v[36:37], v[36:37]
	v_add_f32_e32 v0, v51, v0
	v_add_f32_e32 v0, v40, v0
	v_pk_mul_f32 v[42:43], v[38:39], v[38:39]
	v_add_f32_e32 v0, v41, v0
	v_add_f32_e32 v0, v42, v0
	v_pk_mul_f32 v[32:33], v[28:29], v[28:29]
	v_add_f32_e32 v0, v43, v0
	v_add_f32_e32 v0, v32, v0
	v_pk_mul_f32 v[34:35], v[30:31], v[30:31]
	v_add_f32_e32 v0, v33, v0
	v_add_f32_e32 v0, v34, v0
	v_pk_mul_f32 v[20:21], v[6:7], v[6:7]
	v_add_f32_e32 v0, v35, v0
	v_add_f32_e32 v0, v20, v0
	v_pk_mul_f32 v[26:27], v[22:23], v[22:23]
	v_add_f32_e32 v0, v21, v0
	v_add_f32_e32 v0, v26, v0
	v_pk_mul_f32 v[10:11], v[8:9], v[8:9]
	v_add_f32_e32 v0, v27, v0
	v_add_f32_e32 v0, v10, v0
	v_pk_mul_f32 v[14:15], v[12:13], v[12:13]
	v_add_f32_e32 v0, v11, v0
	v_add_f32_e32 v0, v14, v0
	v_add_f32_e32 v0, v15, v0
	ds_bpermute_b32 v10, v146, v0
	v_readlane_b32 s37, v255, 3
	v_readlane_b32 s36, v255, 18
	v_readlane_b32 s37, v255, 19
	v_readlane_b32 s38, v255, 4
	s_waitcnt lgkmcnt(0)
	v_add_f32_e32 v0, v0, v10
	ds_bpermute_b32 v14, v147, v0
	v_lshl_add_u64 v[10:11], s[26:27], 0, v[110:111]
	v_lshl_add_u64 v[10:11], s[76:77], 1, v[10:11]
	v_readlane_b32 s39, v255, 5
	v_readlane_b32 s40, v255, 6
	s_waitcnt lgkmcnt(0)
	v_add_f32_e32 v0, v0, v14
	v_fmamk_f32 v0, v0, 0x3c000000, v142
	v_mul_f32_e32 v14, 0x4b800000, v0
	v_cmp_gt_f32_e32 vcc, s71, v0
	v_readlane_b32 s41, v255, 7
	v_readlane_b32 s42, v255, 8
	v_cndmask_b32_e32 v0, v0, v14, vcc
	v_rsq_f32_e32 v14, v0
	v_lshlrev_b32_e32 v0, 3, v145
	v_lshl_add_u64 v[10:11], v[10:11], 0, v[0:1]
	v_readlane_b32 s43, v255, 9
	v_mul_f32_e32 v0, 0x45800000, v14
	v_cndmask_b32_e32 v0, v14, v0, vcc
	v_mul_f32_e32 v0, 0x3f24fd5c, v0
	v_readlane_b32 s44, v255, 10
	v_readlane_b32 s45, v255, 11
	v_readlane_b32 s46, v255, 12
	v_readlane_b32 s47, v255, 13
	v_readlane_b32 s48, v255, 14
	v_readlane_b32 s49, v255, 15
	s_waitcnt vmcnt(0)
	v_pk_mul_f32 v[14:15], v[68:69], v[0:1] op_sel_hi:[1,0]
	v_pk_mul_f32 v[16:17], v[16:17], v[0:1] op_sel_hi:[1,0]
	v_pk_mul_f32 v[14:15], v[14:15], v[182:183]
	v_pk_mul_f32 v[16:17], v[16:17], v[184:185]
	v_cvt_pk_bf16_f32 v92, v14, v15
	v_cvt_pk_bf16_f32 v93, v16, v17
	flat_store_dwordx2 v[10:11], v[92:93]
	v_pk_mul_f32 v[14:15], v[60:61], v[0:1] op_sel_hi:[1,0]
	v_pk_mul_f32 v[16:17], v[62:63], v[0:1] op_sel_hi:[1,0]
	v_pk_mul_f32 v[14:15], v[14:15], v[186:187]
	v_pk_mul_f32 v[16:17], v[16:17], v[188:189]
	v_cvt_pk_bf16_f32 v94, v14, v15
	v_cvt_pk_bf16_f32 v95, v16, v17
	flat_store_dwordx2 v[10:11], v[94:95] offset:32
	v_pk_mul_f32 v[14:15], v[52:53], v[0:1] op_sel_hi:[1,0]
	v_pk_mul_f32 v[16:17], v[54:55], v[0:1] op_sel_hi:[1,0]
	v_pk_mul_f32 v[14:15], v[14:15], v[190:191]
	v_pk_mul_f32 v[16:17], v[16:17], v[192:193]
	v_cvt_pk_bf16_f32 v96, v14, v15
	v_cvt_pk_bf16_f32 v97, v16, v17
	flat_store_dwordx2 v[10:11], v[96:97] offset:64
	v_pk_mul_f32 v[14:15], v[44:45], v[0:1] op_sel_hi:[1,0]
	v_pk_mul_f32 v[16:17], v[46:47], v[0:1] op_sel_hi:[1,0]
	v_pk_mul_f32 v[14:15], v[14:15], v[194:195]
	v_pk_mul_f32 v[16:17], v[16:17], v[196:197]
	v_cvt_pk_bf16_f32 v98, v14, v15
	v_cvt_pk_bf16_f32 v99, v16, v17
	flat_store_dwordx2 v[10:11], v[98:99] offset:96
	v_pk_mul_f32 v[14:15], v[36:37], v[0:1] op_sel_hi:[1,0]
	v_pk_mul_f32 v[16:17], v[38:39], v[0:1] op_sel_hi:[1,0]
	v_pk_mul_f32 v[14:15], v[14:15], v[198:199]
	v_pk_mul_f32 v[16:17], v[16:17], v[200:201]
	v_cvt_pk_bf16_f32 v100, v14, v15
	v_cvt_pk_bf16_f32 v101, v16, v17
	flat_store_dwordx2 v[10:11], v[100:101] offset:128
	v_pk_mul_f32 v[14:15], v[28:29], v[0:1] op_sel_hi:[1,0]
	v_pk_mul_f32 v[16:17], v[30:31], v[0:1] op_sel_hi:[1,0]
	v_pk_mul_f32 v[14:15], v[14:15], v[202:203]
	v_pk_mul_f32 v[16:17], v[16:17], v[204:205]
	v_cvt_pk_bf16_f32 v102, v14, v15
	v_cvt_pk_bf16_f32 v103, v16, v17
	flat_store_dwordx2 v[10:11], v[102:103] offset:160
	v_pk_mul_f32 v[14:15], v[6:7], v[0:1] op_sel_hi:[1,0]
	v_pk_mul_f32 v[16:17], v[22:23], v[0:1] op_sel_hi:[1,0]
	v_pk_mul_f32 v[14:15], v[14:15], v[206:207]
	v_pk_mul_f32 v[16:17], v[16:17], v[208:209]
	v_cvt_pk_bf16_f32 v104, v14, v15
	v_cvt_pk_bf16_f32 v105, v16, v17
	flat_store_dwordx2 v[10:11], v[104:105] offset:192
	v_pk_mul_f32 v[14:15], v[8:9], v[0:1] op_sel_hi:[1,0]
	v_pk_mul_f32 v[16:17], v[12:13], v[0:1] op_sel_hi:[1,0]
	v_pk_mul_f32 v[14:15], v[14:15], v[210:211]
	v_pk_mul_f32 v[16:17], v[16:17], v[212:213]
	v_cvt_pk_bf16_f32 v106, v14, v15
	v_cvt_pk_bf16_f32 v107, v16, v17
	flat_store_dwordx2 v[10:11], v[106:107] offset:224
	s_branch .LBB0_1582
